# gdn_intra item start: counted vmcnt(30)/vmcnt(6) instead of vmcnt(0) so the previous item's fragment stores are not drained before the conv-weight and raw q/k/v consumers
# baseline (speedup 1.0000x reference)
; #define LAS __attribute__((address_space(3)))
; DI int TID() { int t = __builtin_amdgcn_workitem_id_x(); asm volatile("" : "+v"(t)); return t; }
; DI void gdn_intra(LAS unsigned char* lds, PP p, int l, int first, int stride) {
;     ...
;     if (first < 2048) { const int tid = TID(); INTRA_PREFETCH(first); INTRA_LOADRAW(first); }
;     for (int item = first; item < 2048; item += stride) {
;     const int tid = TID(), w = tid >> 6, lane = tid & 63, r = lane & 31, h = lane >> 5;
;     { unsigned lb = (unsigned)(size_t)lds; asm volatile("" : "+v"(lb)); lds = (LAS unsigned char*)lb; }
;     LAS bf16_t* Qn = (LAS bf16_t*)(lds + QN_O); LAS bf16_t* Kn = (LAS bf16_t*)(lds + KN_O);
;     LAS bf16_t* XTk = (LAS bf16_t*)(lds + XTK_O); LAS bf16_t* XTv = (LAS bf16_t*)(lds + XTV_O); LAS bf16_t* KT2 = (LAS bf16_t*)(lds + KT2_O);
;     LAS bf16_t* Timg = (LAS bf16_t*)(lds + TIMG_O); LAS float* Mm = (LAS float*)(lds + MM_O); LAS float* At = (LAS float*)(lds + AT_O);
;     LAS float* scb = (LAS float*)(lds + SC_O); LAS float* scg = scb + 64; LAS float* sce = scb + 128; LAS float* scl = scb + 192;
;     LAS float* CW = (LAS float*)(lds + CW_O);
;     const int hd = item >> 8, n = item & 255, tok0 = n * 64;
;     unsigned char* fb = p->ws + O_A + (size_t)item * FRAG_ITEM;
;     unsigned char* ub = p->ws + O_UFR + (size_t)item * UFR_ITEM;
.LBB0_418:
	s_add_u32 s56, s94, 0xb100000
	s_addc_u32 s60, s95, 0
	s_add_u32 s61, s94, 0x12100000
	v_readlane_b32 s2, v254, 49
	s_addc_u32 s64, s95, 0
	v_readlane_b32 s3, v254, 50
	s_and_b64 s[2:3], s[2:3], exec
	s_cselect_b32 s65, 0, 8
	s_add_u32 s82, s94, 0x2da20000
	s_addc_u32 s83, s95, 0
	s_waitcnt vmcnt(24)
	s_branch .LBB0_421

; DI void gdn_intra(LAS unsigned char* lds, PP p, int l, int first, int stride) {
;     ...
;     for (int e = 0; e < 3; ++e) CW[tid + NTHR * e] = Wp[e];
;     if (tid < 64) {
;         const float bl = LG0, al = LG1;
;         const float beta = 1.f / (1.f + __expf(-bl));
;         const float xx = al + p->in[17][l * 8 + hd];
;         const float ex = __expf(fminf(xx, 20.f));
;         const float sp = xx > 20.f ? xx : (ex < 0.05f ? ex * (1.f - ex * (0.5f - ex * (0.33333333f - ex * 0.25f))) : __logf(1.f + ex));
;         float gc = -__expf(p->in[16][l * 8 + hd]) * sp;
.LBB0_421:
	v_mov_b32_e32 v138, v201
	s_ashr_i32 s55, s54, 31
	v_add_u32_e32 v0, 0x21000, v132
	v_add_u32_e32 v23, 0x20c00, v132
	v_add_u32_e32 v35, 0x20e00, v132
	v_lshl_add_u32 v1, v138, 2, v0
	v_add_u32_e32 v22, 0x20d00, v132
	v_add_u32_e32 v30, 0x20f00, v132
	v_cmp_gt_i32_e64 s[22:23], 64, v138
	s_waitcnt vmcnt(30)
	ds_write2st64_b32 v1, v133, v136 offset1:8
	ds_write_b32 v1, v137 offset:4096
	s_and_saveexec_b64 s[2:3], s[22:23]
	s_cbranch_execz .LBB0_430
	s_load_dwordx2 s[24:25], s[0:1], 0x88
	s_ashr_i32 s20, s54, 8
	s_add_i32 s20, s20, s65
	s_ashr_i32 s21, s20, 31
	s_lshl_b64 s[20:21], s[20:21], 2
	s_waitcnt lgkmcnt(0)
	s_add_u32 s24, s24, s20
	s_addc_u32 s25, s25, s21
	s_load_dword s26, s[24:25], 0x0
	s_waitcnt vmcnt(6) lgkmcnt(0)
	s_mov_b32 s24, 0x41a00000
	v_add_f32_e32 v1, s26, v134
	v_cmp_nlt_f32_e32 vcc, s24, v1
	s_and_saveexec_b64 s[26:27], vcc
	s_cbranch_execz .LBB0_428
	v_max_f32_e32 v1, v1, v1
	v_min_f32_e32 v1, 0x41a00000, v1
	v_mul_f32_e32 v1, 0x3fb8aa3b, v1
	v_exp_f32_e32 v2, v1
	s_mov_b32 s24, 0x3d4ccccd
	v_cmp_ngt_f32_e32 vcc, s24, v2
	s_and_saveexec_b64 s[24:25], vcc
	s_xor_b64 s[28:29], exec, s[24:25]
	s_cbranch_execz .LBB0_425
	v_add_f32_e32 v1, 1.0, v2
	v_cmp_gt_f32_e32 vcc, s10, v1
	s_mov_b32 s24, 0x3f317217
	s_nop 0
	v_cndmask_b32_e64 v2, 0, 32, vcc
	v_ldexp_f32 v1, v1, v2
	v_log_f32_e32 v1, v1
	s_nop 0
	v_mul_f32_e32 v2, 0x3f317217, v1
	v_fma_f32 v2, v1, s24, -v2
	v_fmac_f32_e32 v2, 0x3377d1cf, v1
	s_mov_b32 s24, 0x7f800000
	v_fmac_f32_e32 v2, 0x3f317217, v1
	v_cmp_lt_f32_e64 s[24:25], |v1|, s24
	s_nop 1
	v_cndmask_b32_e64 v1, v1, v2, s[24:25]
	v_mov_b32_e32 v2, 0x41b17218
	v_cndmask_b32_e32 v2, 0, v2, vcc
	v_sub_f32_e32 v1, v1, v2

; #define LAS __attribute__((address_space(3)))
; DI void unpack8(u32x4 w, float* f) { f[0] = bflo(w.x); f[1] = bfhi(w.x); f[2] = bflo(w.y); f[3] = bfhi(w.y); f[4] = bflo(w.z); f[5] = bfhi(w.z); f[6] = bflo(w.w); f[7] = bfhi(w.w); }
; DI void lds_barrier() { asm volatile("s_waitcnt lgkmcnt(0)" ::: "memory"); __builtin_amdgcn_s_barrier(); asm volatile("" ::: "memory"); }
; DI void gdn_intra(LAS unsigned char* lds, PP p, int l, int first, int stride) {
;     ...
;     lds_barrier();
; #pragma unroll
;     for (int mat = 0; mat < 3; ++mat) {
; #pragma unroll
;         for (int it = 0; it < 2; ++it) {
;             const int id = tid + NTHR * it, j = id >> 4, o = id & 15;
;             float a[8];
; #pragma unroll
;             for (int i = 0; i < 8; ++i) a[i] = 0.f;
; #pragma unroll
;             for (int kk = 0; kk < 4; ++kk) { const bool ok = tok0 + j - 3 + kk >= 0;
;                 float x[8]; unpack8(R[(mat * 2 + it) * 4 + kk], x);
;                 const f32x4 w0 = *(const LAS f32x4*)(CW + kk * 384 + mat * 128 + o * 8), w1 = *(const LAS f32x4*)(CW + kk * 384 + mat * 128 + o * 8 + 4);
;                 for (int i = 0; i < 4; ++i) { a[i] += ok ? w0[i] * x[i] : 0.f; a[4 + i] += ok ? w1[i] * x[4 + i] : 0.f; } }
.LBB0_430:
	s_or_b64 exec, exec, s[2:3]
	v_and_b32_e32 v28, 15, v138
	v_lshlrev_b32_e32 v20, 5, v28
	s_waitcnt lgkmcnt(0)
	s_barrier
	s_waitcnt vmcnt(6)
	v_add_u32_e32 v26, v0, v20
	ds_read_b128 v[12:15], v26
	ds_read_b128 v[16:19], v26 offset:16
	s_lshl_b32 s2, s54, 6
	s_and_b32 s20, s2, 0x3fc0
	v_ashrrev_i32_e32 v24, 4, v138
	v_add_u32_e32 v21, s20, v24
	v_lshlrev_b32_e32 v0, 16, v38
	v_lshlrev_b32_e32 v4, 16, v36
	v_and_b32_e32 v2, 0xffff0000, v38
	s_waitcnt lgkmcnt(1)
	v_fma_f32 v4, v12, v4, 0
	s_waitcnt lgkmcnt(0)
	v_mul_f32_e32 v5, v16, v0
	v_cmp_lt_i32_e64 s[40:41], 2, v21
	v_and_b32_e32 v1, 0xffff0000, v36
	v_fma_f32 v1, v13, v1, 0
	v_cndmask_b32_e64 v0, 0, v4, s[40:41]
	v_cndmask_b32_e64 v4, 0, v5, s[40:41]
	v_mul_f32_e32 v5, v17, v2
	v_cndmask_b32_e64 v5, 0, v5, s[40:41]
	v_cmp_gt_i32_e64 s[30:31], 3, v21
	v_add_f32_e32 v4, 0, v4
	v_cndmask_b32_e64 v1, 0, v1, s[40:41]
	v_mov_b32_e32 v2, v3
	v_mov_b32_e32 v6, v3
	v_mov_b32_e32 v7, v3
	v_add_f32_e32 v5, 0, v5
	s_and_saveexec_b64 s[2:3], s[30:31]
	s_xor_b64 s[2:3], exec, s[2:3]
	s_or_saveexec_b64 s[2:3], s[2:3]
	v_mov_b32_e32 v8, 0
	s_xor_b64 exec, exec, s[2:3]
	v_lshlrev_b32_e32 v8, 16, v39
	v_lshlrev_b32_e32 v2, 16, v37
	v_fma_f32 v2, v14, v2, 0
	v_mul_f32_e32 v8, v18, v8
	s_or_b64 exec, exec, s[2:3]
	v_add_f32_e32 v12, v6, v8
	v_mov_b64_e32 v[10:11], v[6:7]
	v_mov_b64_e32 v[8:9], v[4:5]
	v_mov_b64_e32 v[6:7], v[2:3]
	v_mov_b64_e32 v[4:5], v[0:1]
	v_mov_b32_e32 v10, v12
	s_and_saveexec_b64 s[2:3], s[30:31]
	s_xor_b64 s[2:3], exec, s[2:3]
	v_add_f32_e32 v7, 0, v3
	s_or_saveexec_b64 s[2:3], s[2:3]
	v_mov_b32_e32 v0, 0
	s_xor_b64 exec, exec, s[2:3]
	v_and_b32_e32 v0, 0xffff0000, v37
	v_and_b32_e32 v1, 0xffff0000, v39
	v_mov_b32_e32 v7, v3
	v_fmac_f32_e32 v7, v15, v0
	v_mul_f32_e32 v0, v19, v1
	s_or_b64 exec, exec, s[2:3]
	ds_read_b128 v[12:15], v26 offset:1536
	ds_read_b128 v[16:19], v26 offset:1552
	v_add_f32_e32 v11, v11, v0
	v_cmp_gt_i32_e64 s[24:25], 2, v21
	s_and_saveexec_b64 s[2:3], s[24:25]
	s_xor_b64 s[2:3], exec, s[2:3]
	v_add_f32_e32 v4, 0, v4
	s_or_saveexec_b64 s[2:3], s[2:3]
	v_mov_b32_e32 v0, 0
	s_xor_b64 exec, exec, s[2:3]
	s_cbranch_execz .LBB0_440
	v_lshlrev_b32_e32 v0, 16, v42
	v_lshlrev_b32_e32 v1, 16, v40
	s_waitcnt lgkmcnt(1)
	v_fmac_f32_e32 v4, v12, v1
	s_waitcnt lgkmcnt(0)
	v_mul_f32_e32 v0, v16, v0
